# speedup vs baseline: 1.0114x; 1.0031x over previous
; __device__ __forceinline__ float bflo(unsigned u) { return __uint_as_float(u << 16); }
; __device__ __forceinline__ float bfhi(unsigned u) { return __uint_as_float(u & 0xffff0000u); }
; __device__ __forceinline__ float silu(float x) { return x / (1.f + __expf(-x)); }
;   __device__ __forceinline__ bfu* z4() const { return (bfu*)(b + L::o_z4); }
; template <bool FOX, int G>
; __device__ __forceinline__ void p3_attn(const Ptrs<G>& w, int seq, int h, int qb, bfu* sm, int kslot) {
;     ...
;   const int zoff = FOX ? 1536 : 1024;
; #pragma unroll
;   for (int j = 0; j < 2; ++j) {
;     const float inv = FOX ? (1.f / lsum[j]) : 1.f;
;     const size_t row = rowbase + qrow0 + 16 * j + c15;
; #pragma unroll
;     for (int dt = 0; dt < 4; ++dt) {
;       bfu* zp = w.z4() + row * 2048 + zoff + h * 64 + 16 * dt + 4 * g;
;       uint2 zz = *(const uint2*)zp;
;       uint2 o;
;       o.x = pack2(O[dt][j][0] * inv * silu(bflo(zz.x)), O[dt][j][1] * inv * silu(bfhi(zz.x)));
;       o.y = pack2(O[dt][j][2] * inv * silu(bflo(zz.y)), O[dt][j][3] * inv * silu(bfhi(zz.y)));
;       *(uint2*)zp = o;
;     }
.LBB0_328:
	s_or_b64 exec, exec, s[16:17]
	v_div_scale_f32 v12, s[0:1], v128, v128, 1.0
	v_rcp_f32_e32 v13, v12
	v_readlane_b32 s12, v253, 38
	v_readlane_b32 s14, v253, 40
	v_readlane_b32 s15, v253, 41
	v_fma_f32 v14, -v12, v13, 1.0
	v_fmac_f32_e32 v13, v14, v13
	v_div_scale_f32 v14, vcc, 1.0, v128, 1.0
	v_mul_f32_e32 v15, v14, v13
	v_fma_f32 v16, -v12, v15, v14
	v_fmac_f32_e32 v15, v16, v13
	v_fma_f32 v12, -v12, v15, v14
	v_div_fmas_f32 v12, v12, v13, v15
	v_lshlrev_b64 v[14:15], 12, v[114:115]
	v_lshl_add_u64 v[14:15], s[14:15], 0, v[14:15]
	s_lshl_b32 s2, s27, 1
	v_lshlrev_b32_e32 v152, 1, v132
	v_lshl_add_u64 v[14:15], v[14:15], 0, s[2:3]
	v_lshl_add_u64 v[14:15], v[14:15], 0, v[152:153]
	v_add_co_u32_e32 v14, vcc, s87, v14
	v_div_fixup_f32 v12, v12, v128, 1.0
	s_nop 0
	v_addc_co_u32_e32 v15, vcc, 0, v15, vcc
	global_load_dwordx2 v[16:17], v[14:15], off offset:1024
	global_load_dwordx2 v[240:241], v[14:15], off offset:1056
	global_load_dwordx2 v[242:243], v[14:15], off offset:1088
	global_load_dwordx2 v[244:245], v[14:15], off offset:1120
	v_readlane_b32 s13, v253, 39
	s_waitcnt vmcnt(3)
	v_lshlrev_b32_e32 v13, 16, v16
	v_and_b32_e32 v16, 0xffff0000, v16
	v_mul_f32_e32 v18, 0xbfb8aa3b, v13
	v_mul_f32_e32 v19, 0xbfb8aa3b, v16
	v_exp_f32_e32 v18, v18
	v_exp_f32_e32 v19, v19
	v_pk_mul_f32 v[20:21], v[60:61], v[12:13] op_sel_hi:[1,0]
	v_pk_add_f32 v[18:19], v[18:19], 1.0 op_sel_hi:[1,0]
	s_nop 0
	v_div_scale_f32 v22, s[0:1], v19, v19, v16
	v_rcp_f32_e32 v23, v22
	s_nop 0
	v_fma_f32 v24, -v22, v23, 1.0
	v_fmac_f32_e32 v23, v24, v23
	v_div_scale_f32 v24, vcc, v16, v19, v16
	v_mul_f32_e32 v25, v24, v23
	v_fma_f32 v26, -v22, v25, v24
	v_fmac_f32_e32 v25, v26, v23
	v_fma_f32 v22, -v22, v25, v24
	v_div_fmas_f32 v22, v22, v23, v25
	v_div_fixup_f32 v19, v22, v19, v16
	v_div_scale_f32 v16, s[0:1], v18, v18, v13
	v_rcp_f32_e32 v22, v16
	s_nop 0
	v_fma_f32 v23, -v16, v22, 1.0
	v_fmac_f32_e32 v22, v23, v22
	v_div_scale_f32 v23, vcc, v13, v18, v13
	v_mul_f32_e32 v24, v23, v22
	v_fma_f32 v25, -v16, v24, v23
	v_fmac_f32_e32 v24, v25, v22
	v_fma_f32 v16, -v16, v24, v23
	v_div_fmas_f32 v16, v16, v22, v24
	v_div_fixup_f32 v18, v16, v18, v13
	v_pk_mul_f32 v[18:19], v[20:21], v[18:19]
	v_lshlrev_b32_e32 v13, 16, v17
	v_and_b32_e32 v17, 0xffff0000, v17
	v_cvt_pk_bf16_f32 v16, v18, v19
	v_mul_f32_e32 v18, 0xbfb8aa3b, v13
	v_mul_f32_e32 v19, 0xbfb8aa3b, v17
	v_exp_f32_e32 v18, v18
	v_exp_f32_e32 v19, v19
	v_pk_mul_f32 v[20:21], v[62:63], v[12:13] op_sel_hi:[1,0]
	v_pk_add_f32 v[18:19], v[18:19], 1.0 op_sel_hi:[1,0]
	s_nop 0
	v_div_scale_f32 v22, s[0:1], v19, v19, v17
	v_rcp_f32_e32 v23, v22
	s_nop 0
	v_fma_f32 v24, -v22, v23, 1.0
	v_fmac_f32_e32 v23, v24, v23
	v_div_scale_f32 v24, vcc, v17, v19, v17
	v_mul_f32_e32 v25, v24, v23
	v_fma_f32 v26, -v22, v25, v24
	v_fmac_f32_e32 v25, v26, v23
	v_fma_f32 v22, -v22, v25, v24
	v_div_fmas_f32 v22, v22, v23, v25
	v_div_fixup_f32 v19, v22, v19, v17
	v_div_scale_f32 v17, s[0:1], v18, v18, v13
	v_rcp_f32_e32 v22, v17
	s_nop 0
	v_fma_f32 v23, -v17, v22, 1.0
	v_fmac_f32_e32 v22, v23, v22
	v_div_scale_f32 v23, vcc, v13, v18, v13
	v_mul_f32_e32 v24, v23, v22
	v_fma_f32 v25, -v17, v24, v23
	v_fmac_f32_e32 v24, v25, v22
	v_fma_f32 v17, -v17, v24, v23
	v_div_fmas_f32 v17, v17, v22, v24
	v_div_fixup_f32 v18, v17, v18, v13
	v_pk_mul_f32 v[18:19], v[20:21], v[18:19]
	s_nop 0
	v_cvt_pk_bf16_f32 v17, v18, v19
	global_store_dwordx2 v[14:15], v[16:17], off offset:1024
	s_waitcnt vmcnt(3)
	v_mov_b32_e32 v16, v240
	v_mov_b32_e32 v17, v241
	v_lshlrev_b32_e32 v13, 16, v16
	v_and_b32_e32 v16, 0xffff0000, v16
	v_mul_f32_e32 v18, 0xbfb8aa3b, v13
	v_mul_f32_e32 v19, 0xbfb8aa3b, v16
	v_exp_f32_e32 v18, v18
	v_exp_f32_e32 v19, v19
	v_pk_mul_f32 v[20:21], v[56:57], v[12:13] op_sel_hi:[1,0]
	v_pk_add_f32 v[18:19], v[18:19], 1.0 op_sel_hi:[1,0]
	s_nop 0
	v_div_scale_f32 v22, s[0:1], v19, v19, v16
	v_rcp_f32_e32 v23, v22
	s_nop 0
	v_fma_f32 v24, -v22, v23, 1.0
	v_fmac_f32_e32 v23, v24, v23
	v_div_scale_f32 v24, vcc, v16, v19, v16
	v_mul_f32_e32 v25, v24, v23
	v_fma_f32 v26, -v22, v25, v24
	v_fmac_f32_e32 v25, v26, v23
	v_fma_f32 v22, -v22, v25, v24
	v_div_fmas_f32 v22, v22, v23, v25
	v_div_fixup_f32 v19, v22, v19, v16
	v_div_scale_f32 v16, s[0:1], v18, v18, v13
	v_rcp_f32_e32 v22, v16
	s_nop 0
	v_fma_f32 v23, -v16, v22, 1.0
	v_fmac_f32_e32 v22, v23, v22
	v_div_scale_f32 v23, vcc, v13, v18, v13
	v_mul_f32_e32 v24, v23, v22
	v_fma_f32 v25, -v16, v24, v23
	v_fmac_f32_e32 v24, v25, v22
	v_fma_f32 v16, -v16, v24, v23
	v_div_fmas_f32 v16, v16, v22, v24
	v_div_fixup_f32 v18, v16, v18, v13
	v_pk_mul_f32 v[18:19], v[20:21], v[18:19]
	v_lshlrev_b32_e32 v13, 16, v17
	v_and_b32_e32 v17, 0xffff0000, v17
	v_cvt_pk_bf16_f32 v16, v18, v19
	v_mul_f32_e32 v18, 0xbfb8aa3b, v13
	v_mul_f32_e32 v19, 0xbfb8aa3b, v17
	v_exp_f32_e32 v18, v18
	v_exp_f32_e32 v19, v19
	v_pk_mul_f32 v[20:21], v[58:59], v[12:13] op_sel_hi:[1,0]
	v_pk_add_f32 v[18:19], v[18:19], 1.0 op_sel_hi:[1,0]
	s_nop 0
	v_div_scale_f32 v22, s[0:1], v19, v19, v17
	v_rcp_f32_e32 v23, v22
	s_nop 0
	v_fma_f32 v24, -v22, v23, 1.0
	v_fmac_f32_e32 v23, v24, v23
	v_div_scale_f32 v24, vcc, v17, v19, v17
	v_mul_f32_e32 v25, v24, v23
	v_fma_f32 v26, -v22, v25, v24
	v_fmac_f32_e32 v25, v26, v23
	v_fma_f32 v22, -v22, v25, v24
	v_div_fmas_f32 v22, v22, v23, v25
	v_div_fixup_f32 v19, v22, v19, v17
	v_div_scale_f32 v17, s[0:1], v18, v18, v13
	v_rcp_f32_e32 v22, v17
	s_nop 0
	v_fma_f32 v23, -v17, v22, 1.0
	v_fmac_f32_e32 v22, v23, v22
	v_div_scale_f32 v23, vcc, v13, v18, v13
	v_mul_f32_e32 v24, v23, v22
	v_fma_f32 v25, -v17, v24, v23
	v_fmac_f32_e32 v24, v25, v22
	v_fma_f32 v17, -v17, v24, v23
	v_div_fmas_f32 v17, v17, v22, v24
	v_div_fixup_f32 v18, v17, v18, v13
	v_pk_mul_f32 v[18:19], v[20:21], v[18:19]
	s_nop 0
	v_cvt_pk_bf16_f32 v17, v18, v19
	global_store_dwordx2 v[14:15], v[16:17], off offset:1056
	s_waitcnt vmcnt(3)
; __device__ __forceinline__ float bflo(unsigned u) { return __uint_as_float(u << 16); }
; __device__ __forceinline__ float bfhi(unsigned u) { return __uint_as_float(u & 0xffff0000u); }
; __device__ __forceinline__ float silu(float x) { return x / (1.f + __expf(-x)); }
;   __device__ __forceinline__ bfu* z4() const { return (bfu*)(b + L::o_z4); }
; template <bool FOX, int G>
; __device__ __forceinline__ void p3_attn(const Ptrs<G>& w, int seq, int h, int qb, bfu* sm, int kslot) {
;     ...
; #pragma unroll
;   for (int j = 0; j < 2; ++j) {
;     const float inv = FOX ? (1.f / lsum[j]) : 1.f;
;     const size_t row = rowbase + qrow0 + 16 * j + c15;
; #pragma unroll
;     for (int dt = 0; dt < 4; ++dt) {
;       bfu* zp = w.z4() + row * 2048 + zoff + h * 64 + 16 * dt + 4 * g;
;       uint2 zz = *(const uint2*)zp;
;       uint2 o;
;       o.x = pack2(O[dt][j][0] * inv * silu(bflo(zz.x)), O[dt][j][1] * inv * silu(bfhi(zz.x)));
;       o.y = pack2(O[dt][j][2] * inv * silu(bflo(zz.y)), O[dt][j][3] * inv * silu(bfhi(zz.y)));
;       *(uint2*)zp = o;
;     }
	v_mov_b32_e32 v16, v242
	v_mov_b32_e32 v17, v243
	v_lshlrev_b32_e32 v13, 16, v16
	v_and_b32_e32 v16, 0xffff0000, v16
	v_mul_f32_e32 v18, 0xbfb8aa3b, v13
	v_mul_f32_e32 v19, 0xbfb8aa3b, v16
	v_exp_f32_e32 v18, v18
	v_exp_f32_e32 v19, v19
	v_pk_mul_f32 v[20:21], v[52:53], v[12:13] op_sel_hi:[1,0]
	v_pk_add_f32 v[18:19], v[18:19], 1.0 op_sel_hi:[1,0]
	s_nop 0
	v_div_scale_f32 v22, s[0:1], v19, v19, v16
	v_rcp_f32_e32 v23, v22
	s_nop 0
	v_fma_f32 v24, -v22, v23, 1.0
	v_fmac_f32_e32 v23, v24, v23
	v_div_scale_f32 v24, vcc, v16, v19, v16
	v_mul_f32_e32 v25, v24, v23
	v_fma_f32 v26, -v22, v25, v24
	v_fmac_f32_e32 v25, v26, v23
	v_fma_f32 v22, -v22, v25, v24
	v_div_fmas_f32 v22, v22, v23, v25
	v_div_fixup_f32 v19, v22, v19, v16
	v_div_scale_f32 v16, s[0:1], v18, v18, v13
	v_rcp_f32_e32 v22, v16
	s_nop 0
	v_fma_f32 v23, -v16, v22, 1.0
	v_fmac_f32_e32 v22, v23, v22
	v_div_scale_f32 v23, vcc, v13, v18, v13
	v_mul_f32_e32 v24, v23, v22
	v_fma_f32 v25, -v16, v24, v23
	v_fmac_f32_e32 v24, v25, v22
	v_fma_f32 v16, -v16, v24, v23
	v_div_fmas_f32 v16, v16, v22, v24
	v_div_fixup_f32 v18, v16, v18, v13
	v_pk_mul_f32 v[18:19], v[20:21], v[18:19]
	v_lshlrev_b32_e32 v13, 16, v17
	v_and_b32_e32 v17, 0xffff0000, v17
	v_cvt_pk_bf16_f32 v16, v18, v19
	v_mul_f32_e32 v18, 0xbfb8aa3b, v13
	v_mul_f32_e32 v19, 0xbfb8aa3b, v17
	v_exp_f32_e32 v18, v18
	v_exp_f32_e32 v19, v19
	v_pk_mul_f32 v[20:21], v[54:55], v[12:13] op_sel_hi:[1,0]
	v_pk_add_f32 v[18:19], v[18:19], 1.0 op_sel_hi:[1,0]
	s_nop 0
	v_div_scale_f32 v22, s[0:1], v19, v19, v17
	v_rcp_f32_e32 v23, v22
	s_nop 0
	v_fma_f32 v24, -v22, v23, 1.0
	v_fmac_f32_e32 v23, v24, v23
	v_div_scale_f32 v24, vcc, v17, v19, v17
	v_mul_f32_e32 v25, v24, v23
	v_fma_f32 v26, -v22, v25, v24
	v_fmac_f32_e32 v25, v26, v23
	v_fma_f32 v22, -v22, v25, v24
	v_div_fmas_f32 v22, v22, v23, v25
	v_div_fixup_f32 v19, v22, v19, v17
	v_div_scale_f32 v17, s[0:1], v18, v18, v13
	v_rcp_f32_e32 v22, v17
	s_nop 0
	v_fma_f32 v23, -v17, v22, 1.0
	v_fmac_f32_e32 v22, v23, v22
	v_div_scale_f32 v23, vcc, v13, v18, v13
	v_mul_f32_e32 v24, v23, v22
	v_fma_f32 v25, -v17, v24, v23
	v_fmac_f32_e32 v24, v25, v22
	v_fma_f32 v17, -v17, v24, v23
	v_div_fmas_f32 v17, v17, v22, v24
	v_div_fixup_f32 v18, v17, v18, v13
	v_pk_mul_f32 v[18:19], v[20:21], v[18:19]
	s_nop 0
	v_cvt_pk_bf16_f32 v17, v18, v19
	global_store_dwordx2 v[14:15], v[16:17], off offset:1088
	s_waitcnt vmcnt(3)
	v_mov_b32_e32 v16, v244
	v_mov_b32_e32 v17, v245
	v_lshlrev_b32_e32 v13, 16, v16
	v_and_b32_e32 v16, 0xffff0000, v16
	v_mul_f32_e32 v18, 0xbfb8aa3b, v13
	v_mul_f32_e32 v19, 0xbfb8aa3b, v16
	v_exp_f32_e32 v18, v18
	v_exp_f32_e32 v19, v19
	v_pk_mul_f32 v[20:21], v[48:49], v[12:13] op_sel_hi:[1,0]
	v_pk_add_f32 v[18:19], v[18:19], 1.0 op_sel_hi:[1,0]
	s_nop 0
	v_div_scale_f32 v22, s[0:1], v19, v19, v16
	v_rcp_f32_e32 v23, v22
	s_nop 0
	v_fma_f32 v24, -v22, v23, 1.0
	v_fmac_f32_e32 v23, v24, v23
	v_div_scale_f32 v24, vcc, v16, v19, v16
	v_mul_f32_e32 v25, v24, v23
	v_fma_f32 v26, -v22, v25, v24
	v_fmac_f32_e32 v25, v26, v23
	v_fma_f32 v22, -v22, v25, v24
	v_div_fmas_f32 v22, v22, v23, v25
	v_div_fixup_f32 v19, v22, v19, v16
	v_div_scale_f32 v16, s[0:1], v18, v18, v13
	v_rcp_f32_e32 v22, v16
	s_nop 0
	v_fma_f32 v23, -v16, v22, 1.0
	v_fmac_f32_e32 v22, v23, v22
	v_div_scale_f32 v23, vcc, v13, v18, v13
	v_mul_f32_e32 v24, v23, v22
	v_fma_f32 v25, -v16, v24, v23
	v_fmac_f32_e32 v24, v25, v22
	v_fma_f32 v16, -v16, v24, v23
	v_div_fmas_f32 v16, v16, v22, v24
	v_div_fixup_f32 v18, v16, v18, v13
	v_pk_mul_f32 v[18:19], v[20:21], v[18:19]
	v_lshlrev_b32_e32 v20, 16, v17
	v_and_b32_e32 v17, 0xffff0000, v17
	v_cvt_pk_bf16_f32 v16, v18, v19
	v_mul_f32_e32 v13, 0xbfb8aa3b, v20
	v_mul_f32_e32 v19, 0xbfb8aa3b, v17
	v_exp_f32_e32 v18, v13
	v_exp_f32_e32 v19, v19
	v_pk_mul_f32 v[12:13], v[50:51], v[12:13] op_sel_hi:[1,0]
	v_pk_add_f32 v[18:19], v[18:19], 1.0 op_sel_hi:[1,0]
	s_nop 0
	v_div_scale_f32 v21, s[0:1], v19, v19, v17
	v_rcp_f32_e32 v22, v21
	s_nop 0
	v_fma_f32 v23, -v21, v22, 1.0
	v_fmac_f32_e32 v22, v23, v22
	v_div_scale_f32 v23, vcc, v17, v19, v17
	v_mul_f32_e32 v24, v23, v22
	v_fma_f32 v25, -v21, v24, v23
	v_fmac_f32_e32 v24, v25, v22
	v_fma_f32 v21, -v21, v24, v23
	v_div_fmas_f32 v21, v21, v22, v24
	v_div_fixup_f32 v19, v21, v19, v17
	v_div_scale_f32 v17, s[0:1], v18, v18, v20
	v_rcp_f32_e32 v21, v17
	s_nop 0
	v_fma_f32 v22, -v17, v21, 1.0
	v_fmac_f32_e32 v21, v22, v21
	v_div_scale_f32 v22, vcc, v20, v18, v20
	v_mul_f32_e32 v23, v22, v21
	v_fma_f32 v24, -v17, v23, v22
	v_fmac_f32_e32 v23, v24, v21
	v_fma_f32 v17, -v17, v23, v22
	v_div_fmas_f32 v17, v17, v21, v23
	v_div_fixup_f32 v18, v17, v18, v20
	v_pk_mul_f32 v[12:13], v[12:13], v[18:19]
	s_nop 0
	v_cvt_pk_bf16_f32 v17, v12, v13
	v_div_scale_f32 v12, s[0:1], v129, v129, 1.0
	v_rcp_f32_e32 v13, v12
	global_store_dwordx2 v[14:15], v[16:17], off offset:1120
	v_fma_f32 v14, -v12, v13, 1.0
	v_fmac_f32_e32 v13, v14, v13
	v_div_scale_f32 v14, vcc, 1.0, v129, 1.0
	v_mul_f32_e32 v15, v14, v13
	v_fma_f32 v16, -v12, v15, v14
	v_fmac_f32_e32 v15, v16, v13
	v_fma_f32 v12, -v12, v15, v14
	v_div_fmas_f32 v12, v12, v13, v15
	v_lshlrev_b64 v[14:15], 12, v[112:113]
	v_lshl_add_u64 v[14:15], s[14:15], 0, v[14:15]
	v_lshl_add_u64 v[14:15], v[14:15], 0, s[2:3]
	v_lshl_add_u64 v[14:15], v[14:15], 0, v[152:153]
	v_add_co_u32_e32 v14, vcc, s87, v14
	v_div_fixup_f32 v12, v12, v129, 1.0
	s_nop 0
	v_addc_co_u32_e32 v15, vcc, 0, v15, vcc
	global_load_dwordx2 v[16:17], v[14:15], off offset:1024
	global_load_dwordx2 v[240:241], v[14:15], off offset:1056
	global_load_dwordx2 v[242:243], v[14:15], off offset:1088
	global_load_dwordx2 v[244:245], v[14:15], off offset:1120
	s_waitcnt vmcnt(3)
; __device__ __forceinline__ float bflo(unsigned u) { return __uint_as_float(u << 16); }
; __device__ __forceinline__ float bfhi(unsigned u) { return __uint_as_float(u & 0xffff0000u); }
; __device__ __forceinline__ float silu(float x) { return x / (1.f + __expf(-x)); }
;   __device__ __forceinline__ bfu* z4() const { return (bfu*)(b + L::o_z4); }
; template <bool FOX, int G>
; __device__ __forceinline__ void p3_attn(const Ptrs<G>& w, int seq, int h, int qb, bfu* sm, int kslot) {
;     ...
;     for (int dt = 0; dt < 4; ++dt) {
;       bfu* zp = w.z4() + row * 2048 + zoff + h * 64 + 16 * dt + 4 * g;
;       uint2 zz = *(const uint2*)zp;
;       uint2 o;
;       o.x = pack2(O[dt][j][0] * inv * silu(bflo(zz.x)), O[dt][j][1] * inv * silu(bfhi(zz.x)));
;       o.y = pack2(O[dt][j][2] * inv * silu(bflo(zz.y)), O[dt][j][3] * inv * silu(bfhi(zz.y)));
;       *(uint2*)zp = o;
;     }
	v_lshlrev_b32_e32 v13, 16, v16
	v_and_b32_e32 v16, 0xffff0000, v16
	v_mul_f32_e32 v18, 0xbfb8aa3b, v13
	v_mul_f32_e32 v19, 0xbfb8aa3b, v16
	v_exp_f32_e32 v18, v18
	v_exp_f32_e32 v19, v19
	v_pk_mul_f32 v[20:21], v[28:29], v[12:13] op_sel_hi:[1,0]
	v_pk_add_f32 v[18:19], v[18:19], 1.0 op_sel_hi:[1,0]
	s_nop 0
	v_div_scale_f32 v22, s[0:1], v19, v19, v16
	v_rcp_f32_e32 v23, v22
	s_nop 0
	v_fma_f32 v24, -v22, v23, 1.0
	v_fmac_f32_e32 v23, v24, v23
	v_div_scale_f32 v24, vcc, v16, v19, v16
	v_mul_f32_e32 v25, v24, v23
	v_fma_f32 v26, -v22, v25, v24
	v_fmac_f32_e32 v25, v26, v23
	v_fma_f32 v22, -v22, v25, v24
	v_div_fmas_f32 v22, v22, v23, v25
	v_div_fixup_f32 v19, v22, v19, v16
	v_div_scale_f32 v16, s[0:1], v18, v18, v13
	v_rcp_f32_e32 v22, v16
	s_nop 0
	v_fma_f32 v23, -v16, v22, 1.0
	v_fmac_f32_e32 v22, v23, v22
	v_div_scale_f32 v23, vcc, v13, v18, v13
	v_mul_f32_e32 v24, v23, v22
	v_fma_f32 v25, -v16, v24, v23
	v_fmac_f32_e32 v24, v25, v22
	v_fma_f32 v16, -v16, v24, v23
	v_div_fmas_f32 v16, v16, v22, v24
	v_div_fixup_f32 v18, v16, v18, v13
	v_pk_mul_f32 v[18:19], v[20:21], v[18:19]
	v_lshlrev_b32_e32 v13, 16, v17
	v_and_b32_e32 v17, 0xffff0000, v17
	v_cvt_pk_bf16_f32 v16, v18, v19
	v_mul_f32_e32 v18, 0xbfb8aa3b, v13
	v_mul_f32_e32 v19, 0xbfb8aa3b, v17
	v_exp_f32_e32 v18, v18
	v_exp_f32_e32 v19, v19
	v_pk_mul_f32 v[20:21], v[30:31], v[12:13] op_sel_hi:[1,0]
	v_pk_add_f32 v[18:19], v[18:19], 1.0 op_sel_hi:[1,0]
	s_nop 0
	v_div_scale_f32 v22, s[0:1], v19, v19, v17
	v_rcp_f32_e32 v23, v22
	s_nop 0
	v_fma_f32 v24, -v22, v23, 1.0
	v_fmac_f32_e32 v23, v24, v23
	v_div_scale_f32 v24, vcc, v17, v19, v17
	v_mul_f32_e32 v25, v24, v23
	v_fma_f32 v26, -v22, v25, v24
	v_fmac_f32_e32 v25, v26, v23
	v_fma_f32 v22, -v22, v25, v24
	v_div_fmas_f32 v22, v22, v23, v25
	v_div_fixup_f32 v19, v22, v19, v17
	v_div_scale_f32 v17, s[0:1], v18, v18, v13
	v_rcp_f32_e32 v22, v17
	s_nop 0
	v_fma_f32 v23, -v17, v22, 1.0
	v_fmac_f32_e32 v22, v23, v22
	v_div_scale_f32 v23, vcc, v13, v18, v13
	v_mul_f32_e32 v24, v23, v22
	v_fma_f32 v25, -v17, v24, v23
	v_fmac_f32_e32 v24, v25, v22
	v_fma_f32 v17, -v17, v24, v23
	v_div_fmas_f32 v17, v17, v22, v24
	v_div_fixup_f32 v18, v17, v18, v13
	v_pk_mul_f32 v[18:19], v[20:21], v[18:19]
	s_nop 0
	v_cvt_pk_bf16_f32 v17, v18, v19
	global_store_dwordx2 v[14:15], v[16:17], off offset:1024
	s_waitcnt vmcnt(3)
	v_mov_b32_e32 v16, v240
	v_mov_b32_e32 v17, v241
	v_lshlrev_b32_e32 v13, 16, v16
	v_and_b32_e32 v16, 0xffff0000, v16
	v_mul_f32_e32 v18, 0xbfb8aa3b, v13
	v_mul_f32_e32 v19, 0xbfb8aa3b, v16
	v_exp_f32_e32 v18, v18
	v_exp_f32_e32 v19, v19
	v_pk_mul_f32 v[8:9], v[8:9], v[12:13] op_sel_hi:[1,0]
	v_pk_add_f32 v[18:19], v[18:19], 1.0 op_sel_hi:[1,0]
	s_nop 0
	v_div_scale_f32 v20, s[0:1], v19, v19, v16
	v_rcp_f32_e32 v21, v20
	s_nop 0
	v_fma_f32 v22, -v20, v21, 1.0
	v_fmac_f32_e32 v21, v22, v21
	v_div_scale_f32 v22, vcc, v16, v19, v16
	v_mul_f32_e32 v23, v22, v21
	v_fma_f32 v24, -v20, v23, v22
	v_fmac_f32_e32 v23, v24, v21
	v_fma_f32 v20, -v20, v23, v22
	v_div_fmas_f32 v20, v20, v21, v23
	v_div_fixup_f32 v19, v20, v19, v16
	v_div_scale_f32 v16, s[0:1], v18, v18, v13
	v_rcp_f32_e32 v20, v16
	s_nop 0
	v_fma_f32 v21, -v16, v20, 1.0
	v_fmac_f32_e32 v20, v21, v20
	v_div_scale_f32 v21, vcc, v13, v18, v13
	v_mul_f32_e32 v22, v21, v20
	v_fma_f32 v23, -v16, v22, v21
	v_fmac_f32_e32 v22, v23, v20
	v_fma_f32 v16, -v16, v22, v21
	v_div_fmas_f32 v16, v16, v20, v22
	v_div_fixup_f32 v18, v16, v18, v13
	v_pk_mul_f32 v[8:9], v[8:9], v[18:19]
	v_and_b32_e32 v13, 0xffff0000, v17
	v_cvt_pk_bf16_f32 v8, v8, v9
	v_lshlrev_b32_e32 v9, 16, v17
	v_mul_f32_e32 v16, 0xbfb8aa3b, v9
	v_mul_f32_e32 v17, 0xbfb8aa3b, v13
	v_exp_f32_e32 v16, v16
	v_exp_f32_e32 v17, v17
	v_pk_mul_f32 v[10:11], v[10:11], v[12:13] op_sel_hi:[1,0]
	v_pk_add_f32 v[16:17], v[16:17], 1.0 op_sel_hi:[1,0]
	s_nop 0
	v_div_scale_f32 v18, s[0:1], v17, v17, v13
	v_rcp_f32_e32 v19, v18
	s_nop 0
	v_fma_f32 v20, -v18, v19, 1.0
	v_fmac_f32_e32 v19, v20, v19
	v_div_scale_f32 v20, vcc, v13, v17, v13
	v_mul_f32_e32 v21, v20, v19
	v_fma_f32 v22, -v18, v21, v20
	v_fmac_f32_e32 v21, v22, v19
	v_fma_f32 v18, -v18, v21, v20
	v_div_fmas_f32 v18, v18, v19, v21
	v_div_fixup_f32 v17, v18, v17, v13
	v_div_scale_f32 v13, s[0:1], v16, v16, v9
	v_rcp_f32_e32 v18, v13
	s_nop 0
	v_fma_f32 v19, -v13, v18, 1.0
	v_fmac_f32_e32 v18, v19, v18
	v_div_scale_f32 v19, vcc, v9, v16, v9
	v_mul_f32_e32 v20, v19, v18
	v_fma_f32 v21, -v13, v20, v19
	v_fmac_f32_e32 v20, v21, v18
	v_fma_f32 v13, -v13, v20, v19
	v_div_fmas_f32 v13, v13, v18, v20
	v_div_fixup_f32 v16, v13, v16, v9
	v_pk_mul_f32 v[10:11], v[10:11], v[16:17]
	s_nop 0
	v_cvt_pk_bf16_f32 v9, v10, v11
	global_store_dwordx2 v[14:15], v[8:9], off offset:1056
	s_waitcnt vmcnt(3)
; __device__ __forceinline__ float bflo(unsigned u) { return __uint_as_float(u << 16); }
; __device__ __forceinline__ float bfhi(unsigned u) { return __uint_as_float(u & 0xffff0000u); }
; __device__ __forceinline__ float silu(float x) { return x / (1.f + __expf(-x)); }
;   __device__ __forceinline__ bfu* z4() const { return (bfu*)(b + L::o_z4); }
; template <bool FOX, int G>
; __device__ __forceinline__ void p3_attn(const Ptrs<G>& w, int seq, int h, int qb, bfu* sm, int kslot) {
;     ...
;     for (int dt = 0; dt < 4; ++dt) {
;       bfu* zp = w.z4() + row * 2048 + zoff + h * 64 + 16 * dt + 4 * g;
;       uint2 zz = *(const uint2*)zp;
;       uint2 o;
;       o.x = pack2(O[dt][j][0] * inv * silu(bflo(zz.x)), O[dt][j][1] * inv * silu(bfhi(zz.x)));
;       o.y = pack2(O[dt][j][2] * inv * silu(bflo(zz.y)), O[dt][j][3] * inv * silu(bfhi(zz.y)));
;       *(uint2*)zp = o;
;     }
	v_mov_b32_e32 v8, v242
	v_mov_b32_e32 v9, v243
	v_lshlrev_b32_e32 v13, 16, v8
	v_and_b32_e32 v8, 0xffff0000, v8
	v_mul_f32_e32 v10, 0xbfb8aa3b, v13
	v_mul_f32_e32 v11, 0xbfb8aa3b, v8
	v_exp_f32_e32 v10, v10
	v_exp_f32_e32 v11, v11
	v_pk_mul_f32 v[4:5], v[4:5], v[12:13] op_sel_hi:[1,0]
	v_pk_mul_f32 v[6:7], v[6:7], v[12:13] op_sel_hi:[1,0]
	v_pk_add_f32 v[10:11], v[10:11], 1.0 op_sel_hi:[1,0]
	s_nop 0
	v_div_scale_f32 v16, s[0:1], v11, v11, v8
	v_rcp_f32_e32 v17, v16
	s_nop 0
	v_fma_f32 v18, -v16, v17, 1.0
	v_fmac_f32_e32 v17, v18, v17
	v_div_scale_f32 v18, vcc, v8, v11, v8
	v_mul_f32_e32 v19, v18, v17
	v_fma_f32 v20, -v16, v19, v18
	v_fmac_f32_e32 v19, v20, v17
	v_fma_f32 v16, -v16, v19, v18
	v_div_fmas_f32 v16, v16, v17, v19
	v_div_fixup_f32 v11, v16, v11, v8
	v_div_scale_f32 v8, s[0:1], v10, v10, v13
	v_rcp_f32_e32 v16, v8
	s_nop 0
	v_fma_f32 v17, -v8, v16, 1.0
	v_fmac_f32_e32 v16, v17, v16
	v_div_scale_f32 v17, vcc, v13, v10, v13
	v_mul_f32_e32 v18, v17, v16
	v_fma_f32 v19, -v8, v18, v17
	v_fmac_f32_e32 v18, v19, v16
	v_fma_f32 v8, -v8, v18, v17
	v_div_fmas_f32 v8, v8, v16, v18
	v_div_fixup_f32 v10, v8, v10, v13
	v_pk_mul_f32 v[4:5], v[4:5], v[10:11]
	v_and_b32_e32 v10, 0xffff0000, v9
	v_cvt_pk_bf16_f32 v4, v4, v5
	v_lshlrev_b32_e32 v5, 16, v9
	v_mul_f32_e32 v8, 0xbfb8aa3b, v5
	v_mul_f32_e32 v9, 0xbfb8aa3b, v10
	v_exp_f32_e32 v8, v8
	v_exp_f32_e32 v9, v9
	s_nop 0
	v_pk_add_f32 v[8:9], v[8:9], 1.0 op_sel_hi:[1,0]
	s_nop 0
	v_div_scale_f32 v11, s[0:1], v9, v9, v10
	v_rcp_f32_e32 v13, v11
	s_nop 0
	v_fma_f32 v16, -v11, v13, 1.0
	v_fmac_f32_e32 v13, v16, v13
	v_div_scale_f32 v16, vcc, v10, v9, v10
	v_mul_f32_e32 v17, v16, v13
	v_fma_f32 v18, -v11, v17, v16
	v_fmac_f32_e32 v17, v18, v13
	v_fma_f32 v11, -v11, v17, v16
	v_div_fmas_f32 v11, v11, v13, v17
	v_div_fixup_f32 v9, v11, v9, v10
	v_div_scale_f32 v10, s[0:1], v8, v8, v5
	v_rcp_f32_e32 v11, v10
	s_nop 0
	v_fma_f32 v13, -v10, v11, 1.0
	v_fmac_f32_e32 v11, v13, v11
	v_div_scale_f32 v13, vcc, v5, v8, v5
	v_mul_f32_e32 v16, v13, v11
	v_fma_f32 v17, -v10, v16, v13
	v_fmac_f32_e32 v16, v17, v11
	v_fma_f32 v10, -v10, v16, v13
	v_div_fmas_f32 v10, v10, v11, v16
	v_div_fixup_f32 v8, v10, v8, v5
	v_pk_mul_f32 v[6:7], v[6:7], v[8:9]
	v_pk_mul_f32 v[0:1], v[0:1], v[12:13] op_sel_hi:[1,0]
	v_cvt_pk_bf16_f32 v5, v6, v7
	global_store_dwordx2 v[14:15], v[4:5], off offset:1088
	s_waitcnt vmcnt(3)
	v_mov_b32_e32 v4, v244
	v_mov_b32_e32 v5, v245
	v_lshlrev_b32_e32 v8, 16, v4
	v_and_b32_e32 v4, 0xffff0000, v4
	v_mul_f32_e32 v6, 0xbfb8aa3b, v8
	v_mul_f32_e32 v7, 0xbfb8aa3b, v4
	v_exp_f32_e32 v6, v6
	v_exp_f32_e32 v7, v7
	s_nop 0
	v_pk_add_f32 v[6:7], v[6:7], 1.0 op_sel_hi:[1,0]
	s_nop 0
	v_div_scale_f32 v9, s[0:1], v7, v7, v4
	v_rcp_f32_e32 v10, v9
	s_nop 0
	v_fma_f32 v11, -v9, v10, 1.0
	v_fmac_f32_e32 v10, v11, v10
	v_div_scale_f32 v11, vcc, v4, v7, v4
	v_mul_f32_e32 v13, v11, v10
	v_fma_f32 v16, -v9, v13, v11
	v_fmac_f32_e32 v13, v16, v10
	v_fma_f32 v9, -v9, v13, v11
	v_div_fmas_f32 v9, v9, v10, v13
	v_div_fixup_f32 v7, v9, v7, v4
	v_div_scale_f32 v4, s[0:1], v6, v6, v8
	v_rcp_f32_e32 v9, v4
	s_nop 0
	v_fma_f32 v10, -v4, v9, 1.0
	v_fmac_f32_e32 v9, v10, v9
	v_div_scale_f32 v10, vcc, v8, v6, v8
	v_mul_f32_e32 v11, v10, v9
	v_fma_f32 v13, -v4, v11, v10
	v_fmac_f32_e32 v11, v13, v9
	v_fma_f32 v4, -v4, v11, v10
	v_div_fmas_f32 v4, v4, v9, v11
	v_div_fixup_f32 v6, v4, v6, v8
	v_pk_mul_f32 v[0:1], v[0:1], v[6:7]
	v_and_b32_e32 v6, 0xffff0000, v5
	v_cvt_pk_bf16_f32 v0, v0, v1
	v_lshlrev_b32_e32 v1, 16, v5
	v_mul_f32_e32 v4, 0xbfb8aa3b, v1
	v_mul_f32_e32 v5, 0xbfb8aa3b, v6
	v_exp_f32_e32 v4, v4
	v_exp_f32_e32 v5, v5
	v_pk_mul_f32 v[2:3], v[2:3], v[12:13] op_sel_hi:[1,0]
	v_pk_add_f32 v[4:5], v[4:5], 1.0 op_sel_hi:[1,0]
	s_nop 0
	v_div_scale_f32 v7, s[0:1], v5, v5, v6
	v_rcp_f32_e32 v8, v7
	s_nop 0
	v_fma_f32 v9, -v7, v8, 1.0
	v_fmac_f32_e32 v8, v9, v8
	v_div_scale_f32 v9, vcc, v6, v5, v6
	v_mul_f32_e32 v10, v9, v8
	v_fma_f32 v11, -v7, v10, v9
	v_fmac_f32_e32 v10, v11, v8
	v_fma_f32 v7, -v7, v10, v9
	v_div_fmas_f32 v7, v7, v8, v10
	v_div_fixup_f32 v5, v7, v5, v6
	v_div_scale_f32 v6, s[0:1], v4, v4, v1
	v_rcp_f32_e32 v7, v6
	s_mov_b64 s[0:1], 0
	v_fma_f32 v8, -v6, v7, 1.0
	v_fmac_f32_e32 v7, v8, v7
	v_div_scale_f32 v8, vcc, v1, v4, v1
	v_mul_f32_e32 v9, v8, v7
	v_fma_f32 v10, -v6, v9, v8
	v_fmac_f32_e32 v9, v10, v7
	v_fma_f32 v6, -v6, v9, v8
	v_div_fmas_f32 v6, v6, v7, v9
	v_div_fixup_f32 v4, v6, v4, v1
	v_pk_mul_f32 v[2:3], v[2:3], v[4:5]
	s_nop 0
	v_cvt_pk_bf16_f32 v1, v2, v3
	global_store_dwordx2 v[14:15], v[0:1], off offset:1120
